# retention epilogue: loads up front in group order with per-group counted vmcnt waits (first group starts as soon as its two loads land)
# speedup vs baseline: 1.0044x; 1.0012x over previous
.LBB0_1187:
	v_lshlrev_b32_e32 v130, 1, v114
	v_lshl_add_u64 v[32:33], v[112:113], 0, v[130:131]
	v_readlane_b32 s8, v253, 40
	v_readlane_b32 s9, v253, 41
	s_lshl_b32 s0, s19, 2
	s_add_u32 s4, s8, s0
	s_addc_u32 s5, s9, 0
	v_lshlrev_b32_e32 v44, 2, v114
	s_nop 0
	global_load_dwordx2 v[182:183], v[32:33], off offset:3072
	global_load_dwordx4 v[198:201], v44, s[4:5]
	global_load_dwordx2 v[184:185], v[32:33], off offset:3088
	global_load_dwordx4 v[202:205], v44, s[4:5] offset:32
	global_load_dwordx2 v[186:187], v[32:33], off offset:3104
	global_load_dwordx4 v[206:209], v44, s[4:5] offset:64
	global_load_dwordx2 v[188:189], v[32:33], off offset:3120
	global_load_dwordx4 v[210:213], v44, s[4:5] offset:96
	global_load_dwordx2 v[190:191], v[32:33], off offset:3136
	global_load_dwordx4 v[214:217], v44, s[4:5] offset:128
	global_load_dwordx2 v[192:193], v[32:33], off offset:3152
	global_load_dwordx4 v[218:221], v44, s[4:5] offset:160
	global_load_dwordx2 v[194:195], v[32:33], off offset:3168
	global_load_dwordx4 v[222:225], v44, s[4:5] offset:192
	global_load_dwordx2 v[196:197], v[32:33], off offset:3184
	global_load_dwordx4 v[226:229], v44, s[4:5] offset:224
	s_nop 7
	v_add_f32_e32 v45, v16, v0
	v_add_f32_e32 v46, v17, v1
	v_add_f32_e32 v45, 0, v45
	v_add_f32_e32 v47, v18, v2
	v_add_f32_e32 v45, v46, v45
	v_add_f32_e32 v48, v19, v3
	v_add_f32_e32 v45, v47, v45
	v_add_f32_e32 v49, v20, v4
	v_add_f32_e32 v45, v48, v45
	v_add_f32_e32 v52, v21, v5
	v_add_f32_e32 v45, v49, v45
	v_pk_add_f32 v[34:35], v[22:23], v[6:7]
	v_add_f32_e32 v45, v52, v45
	v_add_f32_e32 v34, v34, v45
	v_pk_add_f32 v[36:37], v[24:25], v[8:9]
	v_add_f32_e32 v34, v35, v34
	v_add_f32_e32 v34, v36, v34
	v_pk_add_f32 v[38:39], v[26:27], v[10:11]
	v_add_f32_e32 v34, v37, v34
	v_add_f32_e32 v34, v38, v34
	v_pk_add_f32 v[40:41], v[28:29], v[12:13]
	v_add_f32_e32 v34, v39, v34
	v_add_f32_e32 v34, v40, v34
	v_readlane_b32 s4, v253, 36
	s_lshl_b32 s0, s19, 2
	v_pk_add_f32 v[42:43], v[30:31], v[14:15]
	v_add_f32_e32 v34, v41, v34
	v_readlane_b32 s8, v253, 40
	v_add_f32_e32 v34, v42, v34
	v_readlane_b32 s5, v253, 37
	v_readlane_b32 s9, v253, 41
	s_add_u32 s4, s8, s0
	v_lshlrev_b32_e32 v44, 2, v114
	v_add_f32_e32 v34, v43, v34
	s_addc_u32 s5, s9, 0
	v_cmp_lt_i32_e32 vcc, v163, v133
	s_mov_b32 s0, 0x800000
	v_readlane_b32 s6, v253, 38
	v_cndmask_b32_e32 v53, v129, v163, vcc
	v_lshlrev_b32_e32 v64, 2, v53
	ds_bpermute_b32 v35, v64, v34
	v_readlane_b32 s7, v253, 39
	v_readlane_b32 s10, v253, 42
	v_readlane_b32 s11, v253, 43
	s_waitcnt lgkmcnt(0)
	v_add_f32_e32 v34, v34, v35
	v_mul_f32_e32 v52, 0x3c800000, v34
	v_pk_add_f32 v[16:17], v[16:17], v[52:53] op_sel_hi:[1,0] neg_lo:[0,1] neg_hi:[0,1]
	v_pk_add_f32 v[36:37], v[10:11], v[52:53] op_sel_hi:[1,0] neg_lo:[0,1] neg_hi:[0,1]
	v_pk_add_f32 v[26:27], v[26:27], v[52:53] op_sel_hi:[1,0] neg_lo:[0,1] neg_hi:[0,1]
	v_pk_add_f32 v[34:35], v[12:13], v[52:53] op_sel_hi:[1,0] neg_lo:[0,1] neg_hi:[0,1]
	v_pk_add_f32 v[12:13], v[28:29], v[52:53] op_sel_hi:[1,0] neg_lo:[0,1] neg_hi:[0,1]
	v_pk_add_f32 v[28:29], v[14:15], v[52:53] op_sel_hi:[1,0] neg_lo:[0,1] neg_hi:[0,1]
	v_pk_add_f32 v[10:11], v[30:31], v[52:53] op_sel_hi:[1,0] neg_lo:[0,1] neg_hi:[0,1]
	v_pk_add_f32 v[2:3], v[2:3], v[52:53] op_sel_hi:[1,0] neg_lo:[0,1] neg_hi:[0,1]
	v_pk_add_f32 v[0:1], v[0:1], v[52:53] op_sel_hi:[1,0] neg_lo:[0,1] neg_hi:[0,1]
	v_pk_add_f32 v[38:39], v[6:7], v[52:53] op_sel_hi:[1,0] neg_lo:[0,1] neg_hi:[0,1]
	v_pk_add_f32 v[40:41], v[4:5], v[52:53] op_sel_hi:[1,0] neg_lo:[0,1] neg_hi:[0,1]
	v_pk_add_f32 v[30:31], v[8:9], v[52:53] op_sel_hi:[1,0] neg_lo:[0,1] neg_hi:[0,1]
	v_pk_add_f32 v[18:19], v[18:19], v[52:53] op_sel_hi:[1,0] neg_lo:[0,1] neg_hi:[0,1]
	v_pk_add_f32 v[8:9], v[22:23], v[52:53] op_sel_hi:[1,0] neg_lo:[0,1] neg_hi:[0,1]
	v_pk_add_f32 v[14:15], v[20:21], v[52:53] op_sel_hi:[1,0] neg_lo:[0,1] neg_hi:[0,1]
	v_pk_add_f32 v[4:5], v[24:25], v[52:53] op_sel_hi:[1,0] neg_lo:[0,1] neg_hi:[0,1]
	v_mul_f32_e32 v230, v0, v0
	v_mul_f32_e32 v231, v1, v1
	v_mul_f32_e32 v232, v2, v2
	v_mul_f32_e32 v233, v3, v3
	v_fmac_f32_e32 v230, v40, v40
	v_fmac_f32_e32 v231, v41, v41
	v_fmac_f32_e32 v232, v38, v38
	v_fmac_f32_e32 v233, v39, v39
	v_fmac_f32_e32 v230, v30, v30
	v_fmac_f32_e32 v231, v31, v31
	v_fmac_f32_e32 v232, v36, v36
	v_fmac_f32_e32 v233, v37, v37
	v_fmac_f32_e32 v230, v34, v34
	v_fmac_f32_e32 v231, v35, v35
	v_fmac_f32_e32 v232, v28, v28
	v_fmac_f32_e32 v233, v29, v29
	v_fmac_f32_e32 v230, v16, v16
	v_fmac_f32_e32 v231, v17, v17
	v_fmac_f32_e32 v232, v18, v18
	v_fmac_f32_e32 v233, v19, v19
	v_fmac_f32_e32 v230, v14, v14
	v_fmac_f32_e32 v231, v15, v15
	v_fmac_f32_e32 v232, v8, v8
	v_fmac_f32_e32 v233, v9, v9
	v_fmac_f32_e32 v230, v4, v4
	v_fmac_f32_e32 v231, v5, v5
	v_fmac_f32_e32 v232, v26, v26
	v_fmac_f32_e32 v233, v27, v27
	v_fmac_f32_e32 v230, v12, v12
	v_fmac_f32_e32 v231, v13, v13
	v_fmac_f32_e32 v232, v10, v10
	v_fmac_f32_e32 v233, v11, v11
	v_add_f32_e32 v230, v230, v231
	v_add_f32_e32 v232, v232, v233
	v_add_f32_e32 v230, v230, v232
	v_mov_b32_e32 v231, v230
	s_nop 1
	v_permlane32_swap_b32_e32 v230, v231
	v_add_f32_e32 v230, v230, v231
	v_mov_b32_e32 v231, 0x3727c5ac
	v_fmamk_f32 v230, v230, 0x3c800000, v231
	v_rsq_f32_e32 v230, v230
	v_lshl_add_u64 v[246:247], v[32:33], 0, v[130:131]
	s_waitcnt vmcnt(14)
	v_lshlrev_b32_e32 v232, 16, v182
	v_and_b32_e32 v233, 0xffff0000, v182
	v_lshlrev_b32_e32 v234, 16, v183
	v_and_b32_e32 v235, 0xffff0000, v183
	v_mul_f32_e32 v236, 0xbfb8aa3b, v232
	v_mul_f32_e32 v237, 0xbfb8aa3b, v233
	v_mul_f32_e32 v238, 0xbfb8aa3b, v234
	v_mul_f32_e32 v239, 0xbfb8aa3b, v235
	v_exp_f32_e32 v236, v236
	v_exp_f32_e32 v237, v237
	v_exp_f32_e32 v238, v238
	v_exp_f32_e32 v239, v239
	v_mul_f32_e32 v0, v0, v230
	v_mul_f32_e32 v1, v1, v230
	v_mul_f32_e32 v2, v2, v230
	v_mul_f32_e32 v3, v3, v230
	v_add_f32_e32 v236, 1.0, v236
	v_add_f32_e32 v237, 1.0, v237
	v_add_f32_e32 v238, 1.0, v238
	v_add_f32_e32 v239, 1.0, v239
	v_rcp_f32_e32 v236, v236
	v_rcp_f32_e32 v237, v237
	v_rcp_f32_e32 v238, v238
	v_rcp_f32_e32 v239, v239
	v_mul_f32_e32 v0, v0, v198
	v_mul_f32_e32 v1, v1, v199
	v_mul_f32_e32 v2, v2, v200
	v_mul_f32_e32 v3, v3, v201
	v_mul_f32_e32 v232, v232, v236
	v_mul_f32_e32 v233, v233, v237
	v_mul_f32_e32 v234, v234, v238
	v_mul_f32_e32 v235, v235, v239
	v_mul_f32_e32 v0, v0, v232
	v_mul_f32_e32 v1, v1, v233
	v_mul_f32_e32 v2, v2, v234
	v_mul_f32_e32 v3, v3, v235
	v_cvt_pk_bf16_f32 v182, v0, v1
	v_cvt_pk_bf16_f32 v183, v2, v3
	s_waitcnt vmcnt(12)
	v_lshlrev_b32_e32 v232, 16, v184
	v_and_b32_e32 v233, 0xffff0000, v184
	v_lshlrev_b32_e32 v234, 16, v185
	v_and_b32_e32 v235, 0xffff0000, v185
	v_mul_f32_e32 v236, 0xbfb8aa3b, v232
	v_mul_f32_e32 v237, 0xbfb8aa3b, v233
	v_mul_f32_e32 v238, 0xbfb8aa3b, v234
	v_mul_f32_e32 v239, 0xbfb8aa3b, v235
	v_exp_f32_e32 v236, v236
	v_exp_f32_e32 v237, v237
	v_exp_f32_e32 v238, v238
	v_exp_f32_e32 v239, v239
	v_mul_f32_e32 v40, v40, v230
	v_mul_f32_e32 v41, v41, v230
	v_mul_f32_e32 v38, v38, v230
	v_mul_f32_e32 v39, v39, v230
	v_add_f32_e32 v236, 1.0, v236
	v_add_f32_e32 v237, 1.0, v237
	v_add_f32_e32 v238, 1.0, v238
	v_add_f32_e32 v239, 1.0, v239
	v_rcp_f32_e32 v236, v236
	v_rcp_f32_e32 v237, v237
	v_rcp_f32_e32 v238, v238
	v_rcp_f32_e32 v239, v239
	v_mul_f32_e32 v40, v40, v202
	v_mul_f32_e32 v41, v41, v203
	v_mul_f32_e32 v38, v38, v204
	v_mul_f32_e32 v39, v39, v205
	v_mul_f32_e32 v232, v232, v236
	v_mul_f32_e32 v233, v233, v237
	v_mul_f32_e32 v234, v234, v238
	v_mul_f32_e32 v235, v235, v239
	v_mul_f32_e32 v40, v40, v232
	v_mul_f32_e32 v41, v41, v233
	v_mul_f32_e32 v38, v38, v234
	v_mul_f32_e32 v39, v39, v235
	v_cvt_pk_bf16_f32 v184, v40, v41
	v_cvt_pk_bf16_f32 v185, v38, v39
	s_nop 1
	v_permlane32_swap_b32_e32 v182, v184
	v_permlane32_swap_b32_e32 v183, v185
	global_store_dwordx4 v[246:247], v[182:185], off offset:3072
	s_waitcnt vmcnt(11)
	v_lshlrev_b32_e32 v232, 16, v186
	v_and_b32_e32 v233, 0xffff0000, v186
	v_lshlrev_b32_e32 v234, 16, v187
	v_and_b32_e32 v235, 0xffff0000, v187
	v_mul_f32_e32 v236, 0xbfb8aa3b, v232
	v_mul_f32_e32 v237, 0xbfb8aa3b, v233
	v_mul_f32_e32 v238, 0xbfb8aa3b, v234
	v_mul_f32_e32 v239, 0xbfb8aa3b, v235
	v_exp_f32_e32 v236, v236
	v_exp_f32_e32 v237, v237
	v_exp_f32_e32 v238, v238
	v_exp_f32_e32 v239, v239
	v_mul_f32_e32 v30, v30, v230
	v_mul_f32_e32 v31, v31, v230
	v_mul_f32_e32 v36, v36, v230
	v_mul_f32_e32 v37, v37, v230
	v_add_f32_e32 v236, 1.0, v236
	v_add_f32_e32 v237, 1.0, v237
	v_add_f32_e32 v238, 1.0, v238
	v_add_f32_e32 v239, 1.0, v239
	v_rcp_f32_e32 v236, v236
	v_rcp_f32_e32 v237, v237
	v_rcp_f32_e32 v238, v238
	v_rcp_f32_e32 v239, v239
	v_mul_f32_e32 v30, v30, v206
	v_mul_f32_e32 v31, v31, v207
	v_mul_f32_e32 v36, v36, v208
	v_mul_f32_e32 v37, v37, v209
	v_mul_f32_e32 v232, v232, v236
	v_mul_f32_e32 v233, v233, v237
	v_mul_f32_e32 v234, v234, v238
	v_mul_f32_e32 v235, v235, v239
	v_mul_f32_e32 v30, v30, v232
	v_mul_f32_e32 v31, v31, v233
	v_mul_f32_e32 v36, v36, v234
	v_mul_f32_e32 v37, v37, v235
	v_cvt_pk_bf16_f32 v186, v30, v31
	v_cvt_pk_bf16_f32 v187, v36, v37
	s_waitcnt vmcnt(9)
	v_lshlrev_b32_e32 v232, 16, v188
	v_and_b32_e32 v233, 0xffff0000, v188
	v_lshlrev_b32_e32 v234, 16, v189
	v_and_b32_e32 v235, 0xffff0000, v189
	v_mul_f32_e32 v236, 0xbfb8aa3b, v232
	v_mul_f32_e32 v237, 0xbfb8aa3b, v233
	v_mul_f32_e32 v238, 0xbfb8aa3b, v234
	v_mul_f32_e32 v239, 0xbfb8aa3b, v235
	v_exp_f32_e32 v236, v236
	v_exp_f32_e32 v237, v237
	v_exp_f32_e32 v238, v238
	v_exp_f32_e32 v239, v239
	v_mul_f32_e32 v34, v34, v230
	v_mul_f32_e32 v35, v35, v230
	v_mul_f32_e32 v28, v28, v230
	v_mul_f32_e32 v29, v29, v230
	v_add_f32_e32 v236, 1.0, v236
	v_add_f32_e32 v237, 1.0, v237
	v_add_f32_e32 v238, 1.0, v238
	v_add_f32_e32 v239, 1.0, v239
	v_rcp_f32_e32 v236, v236
	v_rcp_f32_e32 v237, v237
	v_rcp_f32_e32 v238, v238
	v_rcp_f32_e32 v239, v239
	v_mul_f32_e32 v34, v34, v210
	v_mul_f32_e32 v35, v35, v211
	v_mul_f32_e32 v28, v28, v212
	v_mul_f32_e32 v29, v29, v213
	v_mul_f32_e32 v232, v232, v236
	v_mul_f32_e32 v233, v233, v237
	v_mul_f32_e32 v234, v234, v238
	v_mul_f32_e32 v235, v235, v239
	v_mul_f32_e32 v34, v34, v232
	v_mul_f32_e32 v35, v35, v233
	v_mul_f32_e32 v28, v28, v234
	v_mul_f32_e32 v29, v29, v235
	v_cvt_pk_bf16_f32 v188, v34, v35
	v_cvt_pk_bf16_f32 v189, v28, v29
	s_nop 1
	v_permlane32_swap_b32_e32 v186, v188
	v_permlane32_swap_b32_e32 v187, v189
	global_store_dwordx4 v[246:247], v[186:189], off offset:3104
	s_waitcnt vmcnt(8)
	v_lshlrev_b32_e32 v232, 16, v190
	v_and_b32_e32 v233, 0xffff0000, v190
	v_lshlrev_b32_e32 v234, 16, v191
	v_and_b32_e32 v235, 0xffff0000, v191
	v_mul_f32_e32 v236, 0xbfb8aa3b, v232
	v_mul_f32_e32 v237, 0xbfb8aa3b, v233
	v_mul_f32_e32 v238, 0xbfb8aa3b, v234
	v_mul_f32_e32 v239, 0xbfb8aa3b, v235
	v_exp_f32_e32 v236, v236
	v_exp_f32_e32 v237, v237
	v_exp_f32_e32 v238, v238
	v_exp_f32_e32 v239, v239
	v_mul_f32_e32 v16, v16, v230
	v_mul_f32_e32 v17, v17, v230
	v_mul_f32_e32 v18, v18, v230
	v_mul_f32_e32 v19, v19, v230
	v_add_f32_e32 v236, 1.0, v236
	v_add_f32_e32 v237, 1.0, v237
	v_add_f32_e32 v238, 1.0, v238
	v_add_f32_e32 v239, 1.0, v239
	v_rcp_f32_e32 v236, v236
	v_rcp_f32_e32 v237, v237
	v_rcp_f32_e32 v238, v238
	v_rcp_f32_e32 v239, v239
	v_mul_f32_e32 v16, v16, v214
	v_mul_f32_e32 v17, v17, v215
	v_mul_f32_e32 v18, v18, v216
	v_mul_f32_e32 v19, v19, v217
	v_mul_f32_e32 v232, v232, v236
	v_mul_f32_e32 v233, v233, v237
	v_mul_f32_e32 v234, v234, v238
	v_mul_f32_e32 v235, v235, v239
	v_mul_f32_e32 v16, v16, v232
	v_mul_f32_e32 v17, v17, v233
	v_mul_f32_e32 v18, v18, v234
	v_mul_f32_e32 v19, v19, v235
	v_cvt_pk_bf16_f32 v190, v16, v17
	v_cvt_pk_bf16_f32 v191, v18, v19
	s_waitcnt vmcnt(6)
	v_lshlrev_b32_e32 v232, 16, v192
	v_and_b32_e32 v233, 0xffff0000, v192
	v_lshlrev_b32_e32 v234, 16, v193
	v_and_b32_e32 v235, 0xffff0000, v193
	v_mul_f32_e32 v236, 0xbfb8aa3b, v232
	v_mul_f32_e32 v237, 0xbfb8aa3b, v233
	v_mul_f32_e32 v238, 0xbfb8aa3b, v234
	v_mul_f32_e32 v239, 0xbfb8aa3b, v235
	v_exp_f32_e32 v236, v236
	v_exp_f32_e32 v237, v237
	v_exp_f32_e32 v238, v238
	v_exp_f32_e32 v239, v239
	v_mul_f32_e32 v14, v14, v230
	v_mul_f32_e32 v15, v15, v230
	v_mul_f32_e32 v8, v8, v230
	v_mul_f32_e32 v9, v9, v230
	v_add_f32_e32 v236, 1.0, v236
	v_add_f32_e32 v237, 1.0, v237
	v_add_f32_e32 v238, 1.0, v238
	v_add_f32_e32 v239, 1.0, v239
	v_rcp_f32_e32 v236, v236
	v_rcp_f32_e32 v237, v237
	v_rcp_f32_e32 v238, v238
	v_rcp_f32_e32 v239, v239
	v_mul_f32_e32 v14, v14, v218
	v_mul_f32_e32 v15, v15, v219
	v_mul_f32_e32 v8, v8, v220
	v_mul_f32_e32 v9, v9, v221
	v_mul_f32_e32 v232, v232, v236
	v_mul_f32_e32 v233, v233, v237
	v_mul_f32_e32 v234, v234, v238
	v_mul_f32_e32 v235, v235, v239
	v_mul_f32_e32 v14, v14, v232
	v_mul_f32_e32 v15, v15, v233
	v_mul_f32_e32 v8, v8, v234
	v_mul_f32_e32 v9, v9, v235
	v_cvt_pk_bf16_f32 v192, v14, v15
	v_cvt_pk_bf16_f32 v193, v8, v9
	s_nop 1
	v_permlane32_swap_b32_e32 v190, v192
	v_permlane32_swap_b32_e32 v191, v193
	global_store_dwordx4 v[246:247], v[190:193], off offset:3136
	s_waitcnt vmcnt(5)
	v_lshlrev_b32_e32 v232, 16, v194
	v_and_b32_e32 v233, 0xffff0000, v194
	v_lshlrev_b32_e32 v234, 16, v195
	v_and_b32_e32 v235, 0xffff0000, v195
	v_mul_f32_e32 v236, 0xbfb8aa3b, v232
	v_mul_f32_e32 v237, 0xbfb8aa3b, v233
	v_mul_f32_e32 v238, 0xbfb8aa3b, v234
	v_mul_f32_e32 v239, 0xbfb8aa3b, v235
	v_exp_f32_e32 v236, v236
	v_exp_f32_e32 v237, v237
	v_exp_f32_e32 v238, v238
	v_exp_f32_e32 v239, v239
	v_mul_f32_e32 v4, v4, v230
	v_mul_f32_e32 v5, v5, v230
	v_mul_f32_e32 v26, v26, v230
	v_mul_f32_e32 v27, v27, v230
	v_add_f32_e32 v236, 1.0, v236
	v_add_f32_e32 v237, 1.0, v237
	v_add_f32_e32 v238, 1.0, v238
	v_add_f32_e32 v239, 1.0, v239
	v_rcp_f32_e32 v236, v236
	v_rcp_f32_e32 v237, v237
	v_rcp_f32_e32 v238, v238
	v_rcp_f32_e32 v239, v239
	v_mul_f32_e32 v4, v4, v222
	v_mul_f32_e32 v5, v5, v223
	v_mul_f32_e32 v26, v26, v224
	v_mul_f32_e32 v27, v27, v225
	v_mul_f32_e32 v232, v232, v236
	v_mul_f32_e32 v233, v233, v237
	v_mul_f32_e32 v234, v234, v238
	v_mul_f32_e32 v235, v235, v239
	v_mul_f32_e32 v4, v4, v232
	v_mul_f32_e32 v5, v5, v233
	v_mul_f32_e32 v26, v26, v234
	v_mul_f32_e32 v27, v27, v235
	v_cvt_pk_bf16_f32 v194, v4, v5
	v_cvt_pk_bf16_f32 v195, v26, v27
	s_waitcnt vmcnt(3)
	v_lshlrev_b32_e32 v232, 16, v196
	v_and_b32_e32 v233, 0xffff0000, v196
	v_lshlrev_b32_e32 v234, 16, v197
	v_and_b32_e32 v235, 0xffff0000, v197
	v_mul_f32_e32 v236, 0xbfb8aa3b, v232
	v_mul_f32_e32 v237, 0xbfb8aa3b, v233
	v_mul_f32_e32 v238, 0xbfb8aa3b, v234
	v_mul_f32_e32 v239, 0xbfb8aa3b, v235
	v_exp_f32_e32 v236, v236
	v_exp_f32_e32 v237, v237
	v_exp_f32_e32 v238, v238
	v_exp_f32_e32 v239, v239
	v_mul_f32_e32 v12, v12, v230
	v_mul_f32_e32 v13, v13, v230
	v_mul_f32_e32 v10, v10, v230
	v_mul_f32_e32 v11, v11, v230
	v_add_f32_e32 v236, 1.0, v236
	v_add_f32_e32 v237, 1.0, v237
	v_add_f32_e32 v238, 1.0, v238
	v_add_f32_e32 v239, 1.0, v239
	v_rcp_f32_e32 v236, v236
	v_rcp_f32_e32 v237, v237
	v_rcp_f32_e32 v238, v238
	v_rcp_f32_e32 v239, v239
	v_mul_f32_e32 v12, v12, v226
	v_mul_f32_e32 v13, v13, v227
	v_mul_f32_e32 v10, v10, v228
	v_mul_f32_e32 v11, v11, v229
	v_mul_f32_e32 v232, v232, v236
	v_mul_f32_e32 v233, v233, v237
	v_mul_f32_e32 v234, v234, v238
	v_mul_f32_e32 v235, v235, v239
	v_mul_f32_e32 v12, v12, v232
	v_mul_f32_e32 v13, v13, v233
	v_mul_f32_e32 v10, v10, v234
	v_mul_f32_e32 v11, v11, v235
	v_cvt_pk_bf16_f32 v196, v12, v13
	v_cvt_pk_bf16_f32 v197, v10, v11
	s_nop 1
	v_permlane32_swap_b32_e32 v194, v196
	v_permlane32_swap_b32_e32 v195, v197
	global_store_dwordx4 v[246:247], v[194:197], off offset:3168
	s_mov_b64 s[4:5], 0
